# MoBA selected-block partial stores widened: v_permlane32_swap of adjacent column groups then 4 dwordx4 stores per set instead of 8 dwordx2 (same bytes, same addresses)
# speedup vs baseline: 1.0027x; 1.0027x over previous
; __device__ __forceinline__ unsigned cvt_pk_bf16(float lo, float hi) { f32x2_t v = {lo, hi}; bf16x2_t b = __builtin_convertvector(v, bf16x2_t); return __builtin_bit_cast(unsigned, b); }
; __device__ __forceinline__ float fast_rcp(float x) { return __builtin_amdgcn_rcpf(x); }
; __device__ __forceinline__ float swap_sum(float v) { auto rr = __builtin_amdgcn_permlane32_swap(__float_as_uint(v), __float_as_uint(v), false, false); return __uint_as_float(rr[0]) + __uint_as_float(rr[1]); }
; __device__ __forceinline__ void moba_partial_store(const f32x16& o0, const f32x16& o1, float m, float l, float slope2, int t, int j, int rs, int b, int h, int hh, bf16_t* PO, float* PML) {
;     const float lt = swap_sum(l), inv = fast_rcp(lt);
;     const size_t pidx = (((size_t)b * SEQ + t) * 8 + h) * 3 + rs;
;     bf16_t* po = PO + pidx * 64;
; #pragma unroll
;     for (int d0 = 0; d0 < 2; ++d0)
; #pragma unroll
;         for (int g = 0; g < 4; ++g) { const int d = 32 * d0 + 8 * g + 4 * hh; const f32x16& o = d0 ? o1 : o0;
;             u32x2 w; w.x = cvt_pk_bf16(o[4 * g] * inv, o[4 * g + 1] * inv); w.y = cvt_pk_bf16(o[4 * g + 2] * inv, o[4 * g + 3] * inv); *(u32x2*)(po + d) = w; }
;     if (hh == 0) { PML[pidx * 2] = m - slope2 * (float)(t - j * 256); PML[pidx * 2 + 1] = lt; }
; }
.LBB0_496:
	s_waitcnt lgkmcnt(0)
	s_barrier
	s_lshl_b32 s1, s1, 8
	s_and_saveexec_b64 s[18:19], s[46:47]
	s_cbranch_execz .LBB0_499
	v_mov_b32_e32 v0, v154
	s_nop 1
	v_permlane32_swap_b32_e32 v154, v0
	v_add_f32_e32 v3, v154, v0
	s_lshl_b64 s[4:5], s[28:29], 17
	v_lshlrev_b32_sdwa v0, v241, v137 dst_sel:DWORD dst_unused:UNUSED_PAD src0_sel:DWORD src1_sel:WORD_0
	v_rcp_f32_e32 v2, v3
	v_lshl_add_u64 v[6:7], s[4:5], 0, v[0:1]
	v_lshrrev_b32_e32 v4, 16, v137
	v_or_b32_e32 v0, s0, v6
	v_mov_b32_e32 v5, v1
	v_mad_u64_u32 v[4:5], s[4:5], v0, 3, v[4:5]
	v_mad_i32_i24 v5, v7, 3, v5
	v_lshlrev_b64 v[6:7], 7, v[4:5]
	v_lshl_add_u64 v[6:7], v[152:153], 0, v[6:7]
	v_mbcnt_lo_u32_b32 v110, -1, 0
	v_mbcnt_hi_u32_b32 v110, -1, v110
	v_and_b32_e32 v110, 32, v110
	v_lshrrev_b32_e32 v110, 2, v110
	v_mov_b32_e32 v111, 0
	v_lshl_add_u64 v[108:109], v[6:7], 0, v[110:111]
	v_mul_f32_e32 v96, v32, v2
	v_mul_f32_e32 v97, v33, v2
	v_mul_f32_e32 v98, v34, v2
	v_mul_f32_e32 v99, v35, v2
	v_cvt_pk_bf16_f32 v100, v96, v97
	v_cvt_pk_bf16_f32 v101, v98, v99
	v_mul_f32_e32 v96, v36, v2
	v_mul_f32_e32 v97, v37, v2
	v_mul_f32_e32 v98, v38, v2
	v_mul_f32_e32 v99, v39, v2
	v_cvt_pk_bf16_f32 v102, v96, v97
	v_cvt_pk_bf16_f32 v103, v98, v99
	s_nop 1
	v_permlane32_swap_b32_e32 v100, v102
	v_permlane32_swap_b32_e32 v101, v103
	global_store_dwordx4 v[108:109], v[100:103], off
	v_mul_f32_e32 v96, v40, v2
	v_mul_f32_e32 v97, v41, v2
	v_mul_f32_e32 v98, v42, v2
	v_mul_f32_e32 v99, v43, v2
	v_cvt_pk_bf16_f32 v104, v96, v97
	v_cvt_pk_bf16_f32 v105, v98, v99
	v_mul_f32_e32 v96, v44, v2
	v_mul_f32_e32 v97, v45, v2
	v_mul_f32_e32 v98, v46, v2
	v_mul_f32_e32 v99, v47, v2
	v_cvt_pk_bf16_f32 v106, v96, v97
	v_cvt_pk_bf16_f32 v107, v98, v99
	s_nop 1
	v_permlane32_swap_b32_e32 v104, v106
	v_permlane32_swap_b32_e32 v105, v107
	global_store_dwordx4 v[108:109], v[104:107], off offset:32
	v_mul_f32_e32 v96, v16, v2
	v_mul_f32_e32 v97, v17, v2
	v_mul_f32_e32 v98, v18, v2
	v_mul_f32_e32 v99, v19, v2
	v_cvt_pk_bf16_f32 v100, v96, v97
	v_cvt_pk_bf16_f32 v101, v98, v99
	v_mul_f32_e32 v96, v20, v2
	v_mul_f32_e32 v97, v21, v2
	v_mul_f32_e32 v98, v22, v2
	v_mul_f32_e32 v99, v23, v2
	v_cvt_pk_bf16_f32 v102, v96, v97
	v_cvt_pk_bf16_f32 v103, v98, v99
	s_nop 1
	v_permlane32_swap_b32_e32 v100, v102
	v_permlane32_swap_b32_e32 v101, v103
	global_store_dwordx4 v[108:109], v[100:103], off offset:64
	v_mul_f32_e32 v96, v24, v2
	v_mul_f32_e32 v97, v25, v2
	v_mul_f32_e32 v98, v26, v2
	v_mul_f32_e32 v99, v27, v2
	v_cvt_pk_bf16_f32 v104, v96, v97
	v_cvt_pk_bf16_f32 v105, v98, v99
	v_mul_f32_e32 v96, v28, v2
	v_mul_f32_e32 v97, v29, v2
	v_mul_f32_e32 v98, v30, v2
	v_mul_f32_e32 v99, v31, v2
	v_cvt_pk_bf16_f32 v106, v96, v97
	v_cvt_pk_bf16_f32 v107, v98, v99
	s_nop 1
	v_permlane32_swap_b32_e32 v104, v106
	v_permlane32_swap_b32_e32 v105, v107
	global_store_dwordx4 v[108:109], v[104:107], off offset:96
	s_and_b64 exec, exec, s[78:79]
	s_cbranch_execz .LBB0_499
	v_sub_u32_sdwa v0, v137, s1 dst_sel:DWORD dst_unused:UNUSED_PAD src0_sel:WORD_0 src1_sel:DWORD
	v_cvt_f32_i32_e32 v0, v0
	v_readlane_b32 s4, v252, 9
	v_readlane_b32 s5, v252, 10
	v_fma_f32 v2, -v132, v0, v134
	s_nop 0
	v_lshl_add_u64 v[4:5], v[4:5], 3, s[4:5]
	global_store_dwordx2 v[4:5], v[2:3], off
.LBB0_499:
	s_or_b64 exec, exec, s[18:19]
	s_and_saveexec_b64 s[18:19], s[44:45]
	v_readlane_b32 s52, v254, 59
	v_readlane_b32 s53, v254, 60
	s_cbranch_execz .LBB0_502
	v_mov_b32_e32 v0, v155
	s_nop 1
	v_permlane32_swap_b32_e32 v155, v0
	v_add_f32_e32 v3, v155, v0
	s_lshl_b64 s[4:5], s[28:29], 17
	v_lshlrev_b32_sdwa v0, v241, v135 dst_sel:DWORD dst_unused:UNUSED_PAD src0_sel:DWORD src1_sel:WORD_0
	v_rcp_f32_e32 v2, v3
	v_lshl_add_u64 v[6:7], s[4:5], 0, v[0:1]
	v_lshrrev_b32_e32 v4, 16, v135
	v_or_b32_e32 v0, s0, v6
	v_mov_b32_e32 v5, v1
	v_mad_u64_u32 v[4:5], s[4:5], v0, 3, v[4:5]
	v_mad_i32_i24 v5, v7, 3, v5
	v_lshlrev_b64 v[6:7], 7, v[4:5]
	v_lshl_add_u64 v[6:7], v[152:153], 0, v[6:7]
	v_mbcnt_lo_u32_b32 v110, -1, 0
	v_mbcnt_hi_u32_b32 v110, -1, v110
	v_and_b32_e32 v110, 32, v110
	v_lshrrev_b32_e32 v110, 2, v110
	v_mov_b32_e32 v111, 0
	v_lshl_add_u64 v[108:109], v[6:7], 0, v[110:111]
	v_mul_f32_e32 v96, v64, v2
	v_mul_f32_e32 v97, v65, v2
	v_mul_f32_e32 v98, v66, v2
	v_mul_f32_e32 v99, v67, v2
	v_cvt_pk_bf16_f32 v100, v96, v97
	v_cvt_pk_bf16_f32 v101, v98, v99
	v_mul_f32_e32 v96, v68, v2
	v_mul_f32_e32 v97, v69, v2
	v_mul_f32_e32 v98, v70, v2
	v_mul_f32_e32 v99, v71, v2
	v_cvt_pk_bf16_f32 v102, v96, v97
	v_cvt_pk_bf16_f32 v103, v98, v99
	s_nop 1
	v_permlane32_swap_b32_e32 v100, v102
	v_permlane32_swap_b32_e32 v101, v103
	global_store_dwordx4 v[108:109], v[100:103], off
	v_mul_f32_e32 v96, v72, v2
	v_mul_f32_e32 v97, v73, v2
	v_mul_f32_e32 v98, v74, v2
	v_mul_f32_e32 v99, v75, v2
	v_cvt_pk_bf16_f32 v104, v96, v97
	v_cvt_pk_bf16_f32 v105, v98, v99
	v_mul_f32_e32 v96, v76, v2
	v_mul_f32_e32 v97, v77, v2
	v_mul_f32_e32 v98, v78, v2
	v_mul_f32_e32 v99, v79, v2
	v_cvt_pk_bf16_f32 v106, v96, v97
	v_cvt_pk_bf16_f32 v107, v98, v99
	s_nop 1
	v_permlane32_swap_b32_e32 v104, v106
	v_permlane32_swap_b32_e32 v105, v107
	global_store_dwordx4 v[108:109], v[104:107], off offset:32
	v_mul_f32_e32 v96, v48, v2
	v_mul_f32_e32 v97, v49, v2
	v_mul_f32_e32 v98, v50, v2
	v_mul_f32_e32 v99, v51, v2
	v_cvt_pk_bf16_f32 v100, v96, v97
	v_cvt_pk_bf16_f32 v101, v98, v99
	v_mul_f32_e32 v96, v52, v2
	v_mul_f32_e32 v97, v53, v2
	v_mul_f32_e32 v98, v54, v2
	v_mul_f32_e32 v99, v55, v2
	v_cvt_pk_bf16_f32 v102, v96, v97
	v_cvt_pk_bf16_f32 v103, v98, v99
	s_nop 1
	v_permlane32_swap_b32_e32 v100, v102
	v_permlane32_swap_b32_e32 v101, v103
	global_store_dwordx4 v[108:109], v[100:103], off offset:64
	v_mul_f32_e32 v96, v56, v2
	v_mul_f32_e32 v97, v57, v2
	v_mul_f32_e32 v98, v58, v2
	v_mul_f32_e32 v99, v59, v2
	v_cvt_pk_bf16_f32 v104, v96, v97
	v_cvt_pk_bf16_f32 v105, v98, v99
	v_mul_f32_e32 v96, v60, v2
	v_mul_f32_e32 v97, v61, v2
	v_mul_f32_e32 v98, v62, v2
	v_mul_f32_e32 v99, v63, v2
	v_cvt_pk_bf16_f32 v106, v96, v97
	v_cvt_pk_bf16_f32 v107, v98, v99
	s_nop 1
	v_permlane32_swap_b32_e32 v104, v106
	v_permlane32_swap_b32_e32 v105, v107
	global_store_dwordx4 v[108:109], v[104:107], off offset:96
	s_and_b64 exec, exec, s[78:79]
	s_cbranch_execz .LBB0_502
	v_sub_u32_sdwa v0, v135, s1 dst_sel:DWORD dst_unused:UNUSED_PAD src0_sel:WORD_0 src1_sel:DWORD
	v_cvt_f32_i32_e32 v0, v0
	v_readlane_b32 s0, v252, 9
	v_readlane_b32 s1, v252, 10
	v_fma_f32 v2, -v132, v0, v136
	s_nop 0
	v_lshl_add_u64 v[4:5], v[4:5], 3, s[0:1]
	global_store_dwordx2 v[4:5], v[2:3], off
